# P0: batched W_in transposition (32 loads in flight per wave instead of serialized load-wait pairs), on top of seam-0 XCD barrier
# speedup vs baseline: 1.0171x; 1.0037x over previous
.Ls0_arrived:
	v_readlane_b32 s10, v249, 0
	s_cmp_lt_i32 s10, 0
	s_cselect_b64 s[2:3], -1, 0
	s_cmp_ge_i32 s10, s96
	s_cselect_b64 s[8:9], -1, 0
	s_or_b64 s[2:3], s[2:3], s[8:9]
	v_and_b32_e32 v2, 63, v188
	s_and_b64 vcc, exec, s[2:3]
	s_cbranch_vccnz .LBB0_26
	v_lshrrev_b32_e32 v3, 6, v188
	v_lshl_add_u32 v1, s10, 3, v3
	s_movk_i32 s2, 0x500
	v_cmp_gt_u32_e32 vcc, s2, v1
	s_and_saveexec_b64 s[8:9], vcc
	s_cbranch_execz .LBB0_25
	v_readfirstlane_b32 s32, v1
	v_and_b32_e32 v4, 63, v188
	v_and_b32_e32 v5, 31, v188
	v_lshlrev_b32_e32 v5, 2, v5
	v_lshrrev_b32_e32 v6, 5, v4
	v_and_b32_e32 v7, 7, v188
	v_lshrrev_b32_e32 v8, 3, v4
	v_lshrrev_b32_e32 v9, 6, v188
	v_lshlrev_b32_e32 v9, 14, v9
	v_mul_u32_u24_e32 v10, 0x84, v6
	v_add3_u32 v10, v10, v5, v9
	v_mul_u32_u24_e32 v11, 0x420, v7
	v_lshl_add_u32 v11, v8, 2, v11
	v_add_u32_e32 v11, v11, v9
	v_lshlrev_b32_e32 v12, 5, v7
	v_lshlrev_b32_e32 v13, 4, v7
.Lxo_item:
	s_sub_u32 s33, s32, 0
	s_mul_hi_u32 s34, s33, 53687092
	s_mul_i32 s39, s34, 80
	s_sub_u32 s35, s33, s39
	s_lshl_b32 s34, s34, 6
	s_lshl_b32 s35, s35, 5
	v_readlane_b32 s50, v249, 15
	v_readlane_b32 s51, v249, 16
	s_movk_i32 s45, 0x2800
	s_movk_i32 s48, 0x800
	s_add_u32 s60, s30, 0x400000
	s_addc_u32 s61, s31, 0
	s_mov_b32 s52, s35
	s_mov_b32 s49, 1
	v_readlane_b32 s54, v249, 13
	v_readlane_b32 s55, v249, 14
	s_lshl_b32 s39, s34, 2
	s_add_u32 s40, s54, s39
	s_addc_u32 s41, s55, 0

.Lxo_ld:
	global_load_dword v16, v14, s[36:37]
	s_add_u32 s36, s36, s38
	s_addc_u32 s37, s37, 0
	global_load_dword v17, v14, s[36:37]
	s_add_u32 s36, s36, s38
	s_addc_u32 s37, s37, 0
	global_load_dword v18, v14, s[36:37]
	s_add_u32 s36, s36, s38
	s_addc_u32 s37, s37, 0
	global_load_dword v19, v14, s[36:37]
	s_add_u32 s36, s36, s38
	s_addc_u32 s37, s37, 0
	global_load_dword v20, v14, s[36:37]
	s_add_u32 s36, s36, s38
	s_addc_u32 s37, s37, 0
	global_load_dword v21, v14, s[36:37]
	s_add_u32 s36, s36, s38
	s_addc_u32 s37, s37, 0
	global_load_dword v22, v14, s[36:37]
	s_add_u32 s36, s36, s38
	s_addc_u32 s37, s37, 0
	global_load_dword v23, v14, s[36:37]
	s_add_u32 s36, s36, s38
	s_addc_u32 s37, s37, 0
	global_load_dword v24, v14, s[36:37]
	s_add_u32 s36, s36, s38
	s_addc_u32 s37, s37, 0
	global_load_dword v25, v14, s[36:37]
	s_add_u32 s36, s36, s38
	s_addc_u32 s37, s37, 0
	global_load_dword v26, v14, s[36:37]
	s_add_u32 s36, s36, s38
	s_addc_u32 s37, s37, 0
	global_load_dword v27, v14, s[36:37]
	s_add_u32 s36, s36, s38
	s_addc_u32 s37, s37, 0
	global_load_dword v28, v14, s[36:37]
	s_add_u32 s36, s36, s38
	s_addc_u32 s37, s37, 0
	global_load_dword v29, v14, s[36:37]
	s_add_u32 s36, s36, s38
	s_addc_u32 s37, s37, 0
	global_load_dword v30, v14, s[36:37]
	s_add_u32 s36, s36, s38
	s_addc_u32 s37, s37, 0
	global_load_dword v31, v14, s[36:37]
	s_add_u32 s36, s36, s38
	s_addc_u32 s37, s37, 0
	global_load_dword v32, v14, s[36:37]
	s_add_u32 s36, s36, s38
	s_addc_u32 s37, s37, 0
	global_load_dword v33, v14, s[36:37]
	s_add_u32 s36, s36, s38
	s_addc_u32 s37, s37, 0
	global_load_dword v34, v14, s[36:37]
	s_add_u32 s36, s36, s38
	s_addc_u32 s37, s37, 0
	global_load_dword v35, v14, s[36:37]
	s_add_u32 s36, s36, s38
	s_addc_u32 s37, s37, 0
	global_load_dword v36, v14, s[36:37]
	s_add_u32 s36, s36, s38
	s_addc_u32 s37, s37, 0
	global_load_dword v37, v14, s[36:37]
	s_add_u32 s36, s36, s38
	s_addc_u32 s37, s37, 0
	global_load_dword v38, v14, s[36:37]
	s_add_u32 s36, s36, s38
	s_addc_u32 s37, s37, 0
	global_load_dword v39, v14, s[36:37]
	s_add_u32 s36, s36, s38
	s_addc_u32 s37, s37, 0
	global_load_dword v40, v14, s[36:37]
	s_add_u32 s36, s36, s38
	s_addc_u32 s37, s37, 0
	global_load_dword v41, v14, s[36:37]
	s_add_u32 s36, s36, s38
	s_addc_u32 s37, s37, 0
	global_load_dword v42, v14, s[36:37]
	s_add_u32 s36, s36, s38
	s_addc_u32 s37, s37, 0
	global_load_dword v43, v14, s[36:37]
	s_add_u32 s36, s36, s38
	s_addc_u32 s37, s37, 0
	global_load_dword v44, v14, s[36:37]
	s_add_u32 s36, s36, s38
	s_addc_u32 s37, s37, 0
	global_load_dword v45, v14, s[36:37]
	s_add_u32 s36, s36, s38
	s_addc_u32 s37, s37, 0
	global_load_dword v46, v14, s[36:37]
	s_add_u32 s36, s36, s38
	s_addc_u32 s37, s37, 0
	global_load_dword v47, v14, s[36:37]
	s_waitcnt vmcnt(31)
	ds_write_b32 v10, v16
	s_waitcnt vmcnt(30)
	ds_write_b32 v10, v17 offset:264
	s_waitcnt vmcnt(29)
	ds_write_b32 v10, v18 offset:528
	s_waitcnt vmcnt(28)
	ds_write_b32 v10, v19 offset:792
	s_waitcnt vmcnt(27)
	ds_write_b32 v10, v20 offset:1056
	s_waitcnt vmcnt(26)
	ds_write_b32 v10, v21 offset:1320
	s_waitcnt vmcnt(25)
	ds_write_b32 v10, v22 offset:1584
	s_waitcnt vmcnt(24)
	ds_write_b32 v10, v23 offset:1848
	s_waitcnt vmcnt(23)
	ds_write_b32 v10, v24 offset:2112
	s_waitcnt vmcnt(22)
	ds_write_b32 v10, v25 offset:2376
	s_waitcnt vmcnt(21)
	ds_write_b32 v10, v26 offset:2640
	s_waitcnt vmcnt(20)
	ds_write_b32 v10, v27 offset:2904
	s_waitcnt vmcnt(19)
	ds_write_b32 v10, v28 offset:3168
	s_waitcnt vmcnt(18)
	ds_write_b32 v10, v29 offset:3432
	s_waitcnt vmcnt(17)
	ds_write_b32 v10, v30 offset:3696
	s_waitcnt vmcnt(16)
	ds_write_b32 v10, v31 offset:3960
	s_waitcnt vmcnt(15)
	ds_write_b32 v10, v32 offset:4224
	s_waitcnt vmcnt(14)
	ds_write_b32 v10, v33 offset:4488
	s_waitcnt vmcnt(13)
	ds_write_b32 v10, v34 offset:4752
	s_waitcnt vmcnt(12)
	ds_write_b32 v10, v35 offset:5016
	s_waitcnt vmcnt(11)
	ds_write_b32 v10, v36 offset:5280
	s_waitcnt vmcnt(10)
	ds_write_b32 v10, v37 offset:5544
	s_waitcnt vmcnt(9)
	ds_write_b32 v10, v38 offset:5808
	s_waitcnt vmcnt(8)
	ds_write_b32 v10, v39 offset:6072
	s_waitcnt vmcnt(7)
	ds_write_b32 v10, v40 offset:6336
	s_waitcnt vmcnt(6)
	ds_write_b32 v10, v41 offset:6600
	s_waitcnt vmcnt(5)
	ds_write_b32 v10, v42 offset:6864
	s_waitcnt vmcnt(4)
	ds_write_b32 v10, v43 offset:7128
	s_waitcnt vmcnt(3)
	ds_write_b32 v10, v44 offset:7392
	s_waitcnt vmcnt(2)
	ds_write_b32 v10, v45 offset:7656
	s_waitcnt vmcnt(1)
	ds_write_b32 v10, v46 offset:7920
	s_waitcnt vmcnt(0)
	ds_write_b32 v10, v47 offset:8184
	s_waitcnt lgkmcnt(0)
	ds_read2_b32 v[56:57], v11 offset0:0 offset1:33
	ds_read2_b32 v[58:59], v11 offset0:66 offset1:99
	ds_read2_b32 v[60:61], v11 offset0:132 offset1:165
	ds_read2_b32 v[62:63], v11 offset0:198 offset1:231
	ds_read2_b32 v[64:65], v11 offset0:8 offset1:41
	ds_read2_b32 v[66:67], v11 offset0:74 offset1:107
	ds_read2_b32 v[68:69], v11 offset0:140 offset1:173
	ds_read2_b32 v[70:71], v11 offset0:206 offset1:239
	s_waitcnt lgkmcnt(4)
	v_pk_mul_f32 v[56:57], v[56:57], v[48:49]
	v_pk_mul_f32 v[58:59], v[58:59], v[50:51]
	v_pk_mul_f32 v[60:61], v[60:61], v[52:53]
	v_pk_mul_f32 v[62:63], v[62:63], v[54:55]
	v_cvt_pk_bf16_f32 v88, v56, v57
	v_cvt_pk_bf16_f32 v89, v58, v59
	v_cvt_pk_bf16_f32 v90, v60, v61
	v_cvt_pk_bf16_f32 v91, v62, v63
	global_store_dwordx4 v15, v[88:91], s[42:43]
	s_add_u32 s42, s42, s44
	s_addc_u32 s43, s43, 0
	ds_read2_b32 v[72:73], v11 offset0:16 offset1:49
	ds_read2_b32 v[74:75], v11 offset0:82 offset1:115
	ds_read2_b32 v[76:77], v11 offset0:148 offset1:181
	ds_read2_b32 v[78:79], v11 offset0:214 offset1:247
	s_waitcnt lgkmcnt(4)
	v_pk_mul_f32 v[64:65], v[64:65], v[48:49]
	v_pk_mul_f32 v[66:67], v[66:67], v[50:51]
	v_pk_mul_f32 v[68:69], v[68:69], v[52:53]
	v_pk_mul_f32 v[70:71], v[70:71], v[54:55]
	v_cvt_pk_bf16_f32 v92, v64, v65
	v_cvt_pk_bf16_f32 v93, v66, v67
	v_cvt_pk_bf16_f32 v94, v68, v69
	v_cvt_pk_bf16_f32 v95, v70, v71
	global_store_dwordx4 v15, v[92:95], s[42:43]
	s_add_u32 s42, s42, s44
	s_addc_u32 s43, s43, 0
	ds_read2_b32 v[80:81], v11 offset0:24 offset1:57
	ds_read2_b32 v[82:83], v11 offset0:90 offset1:123
	ds_read2_b32 v[84:85], v11 offset0:156 offset1:189
	ds_read2_b32 v[86:87], v11 offset0:222 offset1:255
	s_waitcnt lgkmcnt(4)
	v_pk_mul_f32 v[72:73], v[72:73], v[48:49]
	v_pk_mul_f32 v[74:75], v[74:75], v[50:51]
	v_pk_mul_f32 v[76:77], v[76:77], v[52:53]
	v_pk_mul_f32 v[78:79], v[78:79], v[54:55]
	v_cvt_pk_bf16_f32 v96, v72, v73
	v_cvt_pk_bf16_f32 v97, v74, v75
	v_cvt_pk_bf16_f32 v98, v76, v77
	v_cvt_pk_bf16_f32 v99, v78, v79
	global_store_dwordx4 v15, v[96:99], s[42:43]
	s_add_u32 s42, s42, s44
	s_addc_u32 s43, s43, 0
	s_waitcnt lgkmcnt(0)
	v_pk_mul_f32 v[80:81], v[80:81], v[48:49]
	v_pk_mul_f32 v[82:83], v[82:83], v[50:51]
	v_pk_mul_f32 v[84:85], v[84:85], v[52:53]
	v_pk_mul_f32 v[86:87], v[86:87], v[54:55]
	v_cvt_pk_bf16_f32 v100, v80, v81
	v_cvt_pk_bf16_f32 v101, v82, v83
	v_cvt_pk_bf16_f32 v102, v84, v85
	v_cvt_pk_bf16_f32 v103, v86, v87
	global_store_dwordx4 v15, v[100:103], s[42:43]
	s_add_u32 s32, s32, 2048
	s_cmp_lt_u32 s32, 1280
	s_cbranch_scc1 .Lxo_item
